# grid seams: last arriver releases every XCC generation word directly (one hop), leaders poll their own word
# speedup vs baseline: 1.0286x; 1.0055x over previous
.LBB0_190:
	s_andn2_saveexec_b64 s[12:13], s[12:13]
	s_cbranch_execz .LBB0_210
	s_mov_b64 s[12:13], exec
	s_mov_b64 s[100:101], s[10:11]
	buffer_wbl2 sc1
	s_waitcnt lgkmcnt(0)
	s_waitcnt vmcnt(0)
	v_mbcnt_lo_u32_b32 v1, s12, 0
	v_mbcnt_hi_u32_b32 v1, s13, v1
	v_cmp_eq_u32_e32 vcc, 0, v1
	s_and_saveexec_b64 s[14:15], vcc
	s_cbranch_execz .LBB0_193
	s_bcnt1_i32_b64 s12, s[12:13]
	v_mov_b32_e32 v2, 0x4000
	v_mov_b32_e32 v3, s12
	global_atomic_add v2, v2, v3, s[10:11] offset:1024 sc0
.LBB0_193:
	s_or_b64 exec, exec, s[14:15]
	buffer_inv sc1
	v_cvt_f32_u32_e32 v3, v0
	s_waitcnt vmcnt(1)
	v_readfirstlane_b32 s12, v2
	s_add_u32 s14, s6, 0x2400
	s_addc_u32 s15, s7, 0
	v_rcp_iflag_f32_e32 v3, v3
	v_add_u32_e32 v1, s12, v1
	v_add_u32_e32 v4, 1, v1
	s_mov_b64 s[16:17], -1
	v_mul_f32_e32 v2, 0x4f7ffffe, v3
	v_cvt_u32_f32_e32 v2, v2
	v_sub_u32_e32 v3, 0, v0
	v_mul_lo_u32 v3, v3, v2
	v_mul_hi_u32 v3, v2, v3
	v_add_u32_e32 v2, v2, v3
	v_mul_hi_u32 v2, v1, v2
	v_mul_lo_u32 v3, v2, v0
	v_sub_u32_e32 v1, v1, v3
	v_add_u32_e32 v5, 1, v2
	v_cmp_ge_u32_e32 vcc, v1, v0
	v_sub_u32_e32 v3, v1, v0
	s_nop 0
	v_cndmask_b32_e32 v2, v2, v5, vcc
	v_cndmask_b32_e32 v1, v1, v3, vcc
	v_add_u32_e32 v3, 1, v2
	v_cmp_ge_u32_e32 vcc, v1, v0
	s_nop 1
	v_cndmask_b32_e32 v2, v2, v3, vcc
	v_mul_lo_u32 v1, v0, v2
	v_add_u32_e32 v0, v1, v0
	v_cmp_ne_u32_e32 vcc, v4, v0
	v_mov_b64_e32 v[0:1], s[14:15]
	s_and_saveexec_b64 s[12:13], vcc
	s_cbranch_execz .LBB0_205
	v_mov_b32_e32 v0, 0
	global_load_dword v1, v0, s[14:15] sc1
	s_mov_b64 s[20:21], 0
	s_waitcnt vmcnt(0)
	v_cmp_eq_u32_e32 vcc, v1, v2
	s_and_saveexec_b64 s[18:19], vcc
	s_cbranch_execz .LBB0_204
	s_add_u32 s16, s10, 0x1200
	s_addc_u32 s17, s11, 0
	s_mov_b32 s30, 1
	s_mov_b64 s[10:11], 0
	s_branch .LBB0_197

.LBB0_205:
	s_or_b64 exec, exec, s[12:13]
	s_and_saveexec_b64 s[10:11], s[16:17]
	s_cbranch_execz .LBB0_207
	v_mov_b32_e32 v2, 1
	v_mov_b32_e32 v0, 0x3400
	global_atomic_add v0, v2, s[100:101] offset:0
	global_atomic_add v0, v2, s[100:101] offset:256
	global_atomic_add v0, v2, s[100:101] offset:512
	global_atomic_add v0, v2, s[100:101] offset:768
	global_atomic_add v0, v2, s[100:101] offset:1024
	global_atomic_add v0, v2, s[100:101] offset:1280
	global_atomic_add v0, v2, s[100:101] offset:1536
	global_atomic_add v0, v2, s[100:101] offset:1792
	global_atomic_add v0, v2, s[100:101] offset:2048
	global_atomic_add v0, v2, s[100:101] offset:2304
	global_atomic_add v0, v2, s[100:101] offset:2560
	global_atomic_add v0, v2, s[100:101] offset:2816
	global_atomic_add v0, v2, s[100:101] offset:3072
	global_atomic_add v0, v2, s[100:101] offset:3328
	global_atomic_add v0, v2, s[100:101] offset:3584
	global_atomic_add v0, v2, s[100:101] offset:3840
.LBB0_207:
	s_or_b64 exec, exec, s[10:11]
	s_mov_b64 s[10:11], exec
	v_mbcnt_lo_u32_b32 v0, s10, 0
	v_mbcnt_hi_u32_b32 v0, s11, v0
	v_cmp_eq_u32_e32 vcc, 0, v0
	s_and_saveexec_b64 s[12:13], vcc
	s_cbranch_execz .LBB0_209
	s_bcnt1_i32_b64 s10, s[10:11]
	v_mov_b32_e32 v0, 0x2000
	v_mov_b32_e32 v1, s10
.LBB0_209:
	s_or_b64 exec, exec, s[12:13]
	s_waitcnt vmcnt(0)

.LBB0_297:
	s_andn2_saveexec_b64 s[12:13], s[12:13]
	s_cbranch_execz .LBB0_317
	s_mov_b64 s[12:13], exec
	s_mov_b64 s[100:101], s[6:7]
	buffer_wbl2 sc1
	s_waitcnt lgkmcnt(0)
	s_waitcnt vmcnt(0)
	v_mbcnt_lo_u32_b32 v1, s12, 0
	v_mbcnt_hi_u32_b32 v1, s13, v1
	v_cmp_eq_u32_e32 vcc, 0, v1
	s_and_saveexec_b64 s[14:15], vcc
	s_cbranch_execz .LBB0_300
	s_bcnt1_i32_b64 s12, s[12:13]
	v_mov_b32_e32 v2, s12
	v_mov_b32_e32 v3, 0x4000
	global_atomic_add v2, v3, v2, s[6:7] offset:1024 sc0
.LBB0_300:
	s_or_b64 exec, exec, s[14:15]
	buffer_inv sc1
	v_cvt_f32_u32_e32 v3, v0
	s_waitcnt vmcnt(1)
	v_readfirstlane_b32 s12, v2
	s_mov_b64 s[16:17], -1
	v_rcp_iflag_f32_e32 v3, v3
	v_add_u32_e32 v1, s12, v1
	v_add_u32_e32 v4, 1, v1
	s_add_u32 s12, s10, 0x2400
	v_mul_f32_e32 v2, 0x4f7ffffe, v3
	v_cvt_u32_f32_e32 v2, v2
	v_sub_u32_e32 v3, 0, v0
	s_addc_u32 s13, s11, 0
	v_mul_lo_u32 v3, v3, v2
	v_mul_hi_u32 v3, v2, v3
	v_add_u32_e32 v2, v2, v3
	v_mul_hi_u32 v2, v1, v2
	v_mul_lo_u32 v3, v2, v0
	v_sub_u32_e32 v1, v1, v3
	v_add_u32_e32 v5, 1, v2
	v_cmp_ge_u32_e32 vcc, v1, v0
	v_sub_u32_e32 v3, v1, v0
	s_nop 0
	v_cndmask_b32_e32 v2, v2, v5, vcc
	v_cndmask_b32_e32 v1, v1, v3, vcc
	v_add_u32_e32 v3, 1, v2
	v_cmp_ge_u32_e32 vcc, v1, v0
	s_nop 1
	v_cndmask_b32_e32 v2, v2, v3, vcc
	v_mul_lo_u32 v1, v0, v2
	v_add_u32_e32 v0, v1, v0
	v_cmp_ne_u32_e32 vcc, v4, v0
	v_mov_b64_e32 v[0:1], s[12:13]
	s_and_saveexec_b64 s[14:15], vcc
	s_cbranch_execz .LBB0_312
	global_load_dword v0, v169, s[12:13] sc1
	s_mov_b64 s[20:21], 0
	s_waitcnt vmcnt(0)
	v_cmp_eq_u32_e32 vcc, v0, v2
	s_and_saveexec_b64 s[18:19], vcc
	s_cbranch_execz .LBB0_311
	s_add_u32 s16, s6, 0x1200
	s_addc_u32 s17, s7, 0
	s_mov_b32 s26, 1
	s_mov_b64 s[6:7], 0
	s_branch .LBB0_304

.LBB0_312:
	s_or_b64 exec, exec, s[14:15]
	s_and_saveexec_b64 s[6:7], s[16:17]
	s_cbranch_execz .LBB0_314
	v_mov_b32_e32 v0, 0x3400
	global_atomic_add v0, v227, s[100:101] offset:0
	global_atomic_add v0, v227, s[100:101] offset:256
	global_atomic_add v0, v227, s[100:101] offset:512
	global_atomic_add v0, v227, s[100:101] offset:768
	global_atomic_add v0, v227, s[100:101] offset:1024
	global_atomic_add v0, v227, s[100:101] offset:1280
	global_atomic_add v0, v227, s[100:101] offset:1536
	global_atomic_add v0, v227, s[100:101] offset:1792
	global_atomic_add v0, v227, s[100:101] offset:2048
	global_atomic_add v0, v227, s[100:101] offset:2304
	global_atomic_add v0, v227, s[100:101] offset:2560
	global_atomic_add v0, v227, s[100:101] offset:2816
	global_atomic_add v0, v227, s[100:101] offset:3072
	global_atomic_add v0, v227, s[100:101] offset:3328
	global_atomic_add v0, v227, s[100:101] offset:3584
	global_atomic_add v0, v227, s[100:101] offset:3840
.LBB0_314:
	s_or_b64 exec, exec, s[6:7]
	s_mov_b64 s[6:7], exec
	v_mbcnt_lo_u32_b32 v0, s6, 0
	v_mbcnt_hi_u32_b32 v0, s7, v0
	v_cmp_eq_u32_e32 vcc, 0, v0
	s_and_saveexec_b64 s[12:13], vcc
	s_cbranch_execz .LBB0_316
	s_bcnt1_i32_b64 s6, s[6:7]
	v_mov_b32_e32 v0, s6
	v_mov_b32_e32 v1, 0x2000
.LBB0_316:
	s_or_b64 exec, exec, s[12:13]
	s_waitcnt vmcnt(0)

.LBB0_446:
	s_or_b64 exec, exec, s[6:7]
	s_mov_b64 s[6:7], exec
	v_mbcnt_lo_u32_b32 v0, s6, 0
	v_mbcnt_hi_u32_b32 v0, s7, v0
	v_cmp_eq_u32_e32 vcc, 0, v0
	s_and_saveexec_b64 s[12:13], vcc
	s_cbranch_execz .LBB0_448
	s_bcnt1_i32_b64 s6, s[6:7]
	v_mov_b32_e32 v0, s6
	v_mov_b32_e32 v1, 0x2000
.LBB0_448:
	s_or_b64 exec, exec, s[12:13]
	s_waitcnt vmcnt(0)

.LBB0_516:
	s_or_b64 exec, exec, s[6:7]
	s_mov_b64 s[6:7], exec
	v_mbcnt_lo_u32_b32 v0, s6, 0
	v_mbcnt_hi_u32_b32 v0, s7, v0
	v_cmp_eq_u32_e32 vcc, 0, v0
	s_and_saveexec_b64 s[12:13], vcc
	s_cbranch_execz .LBB0_518
	s_bcnt1_i32_b64 s6, s[6:7]
	v_mov_b32_e32 v0, s6
	v_mov_b32_e32 v1, 0x2000
.LBB0_518:
	s_or_b64 exec, exec, s[12:13]
	s_waitcnt vmcnt(0)

.LBB0_575:
	s_or_b64 exec, exec, s[6:7]
	s_mov_b64 s[6:7], exec
	v_mbcnt_lo_u32_b32 v0, s6, 0
	v_mbcnt_hi_u32_b32 v0, s7, v0
	v_cmp_eq_u32_e32 vcc, 0, v0
	s_and_saveexec_b64 s[12:13], vcc
	s_cbranch_execz .LBB0_577
	s_bcnt1_i32_b64 s6, s[6:7]
	v_mov_b32_e32 v0, s6
	v_mov_b32_e32 v1, 0x2000
.LBB0_577:
	s_or_b64 exec, exec, s[12:13]
	s_waitcnt vmcnt(0)

.LBB0_634:
	s_or_b64 exec, exec, s[6:7]
	s_mov_b64 s[6:7], exec
	v_mbcnt_lo_u32_b32 v0, s6, 0
	v_mbcnt_hi_u32_b32 v0, s7, v0
	v_cmp_eq_u32_e32 vcc, 0, v0
	s_and_saveexec_b64 s[12:13], vcc
	s_cbranch_execz .LBB0_636
	s_bcnt1_i32_b64 s6, s[6:7]
	v_mov_b32_e32 v0, s6
	v_mov_b32_e32 v1, 0x2000
.LBB0_636:
	s_or_b64 exec, exec, s[12:13]
	s_waitcnt vmcnt(0)

.LBB0_720:
	s_or_b64 exec, exec, s[6:7]
	s_mov_b64 s[6:7], exec
	v_mbcnt_lo_u32_b32 v0, s6, 0
	v_mbcnt_hi_u32_b32 v0, s7, v0
	v_cmp_eq_u32_e32 vcc, 0, v0
	s_and_saveexec_b64 s[12:13], vcc
	s_cbranch_execz .LBB0_722
	s_bcnt1_i32_b64 s6, s[6:7]
	v_mov_b32_e32 v0, s6
	v_mov_b32_e32 v1, 0x2000
.LBB0_722:
	s_or_b64 exec, exec, s[12:13]
	s_waitcnt vmcnt(0)

.LBB0_799:
	s_andn2_saveexec_b64 s[14:15], s[14:15]
	s_cbranch_execz .LBB0_819
	s_mov_b64 s[14:15], exec
	s_mov_b64 s[100:101], s[6:7]
	buffer_wbl2 sc1
	s_waitcnt lgkmcnt(0)
	s_waitcnt vmcnt(0)
	v_mbcnt_lo_u32_b32 v1, s14, 0
	v_mbcnt_hi_u32_b32 v1, s15, v1
	v_cmp_eq_u32_e32 vcc, 0, v1
	s_and_saveexec_b64 s[16:17], vcc
	s_cbranch_execz .LBB0_802
	s_bcnt1_i32_b64 s14, s[14:15]
	v_mov_b32_e32 v2, s14
	v_mov_b32_e32 v3, 0x4000
	global_atomic_add v2, v3, v2, s[6:7] offset:1024 sc0
.LBB0_802:
	s_or_b64 exec, exec, s[16:17]
	buffer_inv sc1
	v_cvt_f32_u32_e32 v3, v0
	s_waitcnt vmcnt(1)
	v_readfirstlane_b32 s14, v2
	s_mov_b64 s[18:19], -1
	v_rcp_iflag_f32_e32 v3, v3
	v_add_u32_e32 v1, s14, v1
	v_add_u32_e32 v4, 1, v1
	s_add_u32 s14, s12, 0x2400
	v_mul_f32_e32 v2, 0x4f7ffffe, v3
	v_cvt_u32_f32_e32 v2, v2
	v_sub_u32_e32 v3, 0, v0
	s_addc_u32 s15, s13, 0
	v_mul_lo_u32 v3, v3, v2
	v_mul_hi_u32 v3, v2, v3
	v_add_u32_e32 v2, v2, v3
	v_mul_hi_u32 v2, v1, v2
	v_mul_lo_u32 v3, v2, v0
	v_sub_u32_e32 v1, v1, v3
	v_add_u32_e32 v5, 1, v2
	v_cmp_ge_u32_e32 vcc, v1, v0
	v_sub_u32_e32 v3, v1, v0
	s_nop 0
	v_cndmask_b32_e32 v2, v2, v5, vcc
	v_cndmask_b32_e32 v1, v1, v3, vcc
	v_add_u32_e32 v3, 1, v2
	v_cmp_ge_u32_e32 vcc, v1, v0
	s_nop 1
	v_cndmask_b32_e32 v2, v2, v3, vcc
	v_mul_lo_u32 v1, v0, v2
	v_add_u32_e32 v0, v1, v0
	v_cmp_ne_u32_e32 vcc, v4, v0
	v_mov_b64_e32 v[0:1], s[14:15]
	s_and_saveexec_b64 s[16:17], vcc
	s_cbranch_execz .LBB0_814
	global_load_dword v0, v169, s[14:15] sc1
	s_mov_b64 s[22:23], 0
	s_waitcnt vmcnt(0)
	v_cmp_eq_u32_e32 vcc, v0, v2
	s_and_saveexec_b64 s[20:21], vcc
	s_cbranch_execz .LBB0_813
	s_add_u32 s18, s6, 0x1200
	s_addc_u32 s19, s7, 0
	s_mov_b32 s26, 1
	s_mov_b64 s[6:7], 0
	s_branch .LBB0_806

.LBB0_814:
	s_or_b64 exec, exec, s[16:17]
	s_and_saveexec_b64 s[6:7], s[18:19]
	s_cbranch_execz .LBB0_816
	v_mov_b32_e32 v0, 0x3400
	global_atomic_add v0, v227, s[100:101] offset:0
	global_atomic_add v0, v227, s[100:101] offset:256
	global_atomic_add v0, v227, s[100:101] offset:512
	global_atomic_add v0, v227, s[100:101] offset:768
	global_atomic_add v0, v227, s[100:101] offset:1024
	global_atomic_add v0, v227, s[100:101] offset:1280
	global_atomic_add v0, v227, s[100:101] offset:1536
	global_atomic_add v0, v227, s[100:101] offset:1792
	global_atomic_add v0, v227, s[100:101] offset:2048
	global_atomic_add v0, v227, s[100:101] offset:2304
	global_atomic_add v0, v227, s[100:101] offset:2560
	global_atomic_add v0, v227, s[100:101] offset:2816
	global_atomic_add v0, v227, s[100:101] offset:3072
	global_atomic_add v0, v227, s[100:101] offset:3328
	global_atomic_add v0, v227, s[100:101] offset:3584
	global_atomic_add v0, v227, s[100:101] offset:3840
.LBB0_816:
	s_or_b64 exec, exec, s[6:7]
	s_mov_b64 s[6:7], exec
	v_mbcnt_lo_u32_b32 v0, s6, 0
	v_mbcnt_hi_u32_b32 v0, s7, v0
	v_cmp_eq_u32_e32 vcc, 0, v0
	s_and_saveexec_b64 s[14:15], vcc
	s_cbranch_execz .LBB0_818
	s_bcnt1_i32_b64 s6, s[6:7]
	v_mov_b32_e32 v0, s6
	v_mov_b32_e32 v1, 0x2000
.LBB0_818:
	s_or_b64 exec, exec, s[14:15]
	s_waitcnt vmcnt(0)

.LBB0_949:
	s_or_b64 exec, exec, s[6:7]
	s_mov_b64 s[6:7], exec
	v_mbcnt_lo_u32_b32 v0, s6, 0
	v_mbcnt_hi_u32_b32 v0, s7, v0
	v_cmp_eq_u32_e32 vcc, 0, v0
	s_and_saveexec_b64 s[12:13], vcc
	s_cbranch_execz .LBB0_211
	s_bcnt1_i32_b64 s6, s[6:7]
	v_mov_b32_e32 v0, s6
	v_mov_b32_e32 v1, 0x2000
	s_branch .LBB0_211

	.amdhsa_kernel _ZN2mk6mk_fwdENS_4ArgsE
		.amdhsa_group_segment_fixed_size 0
		.amdhsa_private_segment_fixed_size 0
		.amdhsa_kernarg_size 408
		.amdhsa_user_sgpr_count 2
		.amdhsa_user_sgpr_dispatch_ptr 0
		.amdhsa_user_sgpr_queue_ptr 0
		.amdhsa_user_sgpr_kernarg_segment_ptr 1
		.amdhsa_user_sgpr_dispatch_id 0
		.amdhsa_user_sgpr_kernarg_preload_length 0
		.amdhsa_user_sgpr_kernarg_preload_offset 0
		.amdhsa_user_sgpr_private_segment_size 0
		.amdhsa_uses_dynamic_stack 0
		.amdhsa_enable_private_segment 0
		.amdhsa_system_sgpr_workgroup_id_x 1
		.amdhsa_system_sgpr_workgroup_id_y 0
		.amdhsa_system_sgpr_workgroup_id_z 0
		.amdhsa_system_sgpr_workgroup_info 0
		.amdhsa_system_vgpr_workitem_id 2
		.amdhsa_next_free_vgpr 256
		.amdhsa_next_free_sgpr 102
		.amdhsa_accum_offset 256
		.amdhsa_reserve_vcc 1
		.amdhsa_float_round_mode_32 0
		.amdhsa_float_round_mode_16_64 0
		.amdhsa_float_denorm_mode_32 3
		.amdhsa_float_denorm_mode_16_64 3
		.amdhsa_dx10_clamp 1
		.amdhsa_ieee_mode 1
		.amdhsa_fp16_overflow 0
		.amdhsa_tg_split 0
		.amdhsa_exception_fp_ieee_invalid_op 0
		.amdhsa_exception_fp_denorm_src 0
		.amdhsa_exception_fp_ieee_div_zero 0
		.amdhsa_exception_fp_ieee_overflow 0
		.amdhsa_exception_fp_ieee_underflow 0
		.amdhsa_exception_fp_ieee_inexact 0
		.amdhsa_exception_int_div_zero 0
	.end_amdhsa_kernel

amdhsa.kernels:
  - .agpr_count:     0
    .args:
      - .offset:         0
        .size:           152
        .value_kind:     by_value
      - .offset:         152
        .size:           4
        .value_kind:     hidden_block_count_x
      - .offset:         156
        .size:           4
        .value_kind:     hidden_block_count_y
      - .offset:         160
        .size:           4
        .value_kind:     hidden_block_count_z
      - .offset:         164
        .size:           2
        .value_kind:     hidden_group_size_x
      - .offset:         166
        .size:           2
        .value_kind:     hidden_group_size_y
      - .offset:         168
        .size:           2
        .value_kind:     hidden_group_size_z
      - .offset:         170
        .size:           2
        .value_kind:     hidden_remainder_x
      - .offset:         172
        .size:           2
        .value_kind:     hidden_remainder_y
      - .offset:         174
        .size:           2
        .value_kind:     hidden_remainder_z
      - .offset:         192
        .size:           8
        .value_kind:     hidden_global_offset_x
      - .offset:         200
        .size:           8
        .value_kind:     hidden_global_offset_y
      - .offset:         208
        .size:           8
        .value_kind:     hidden_global_offset_z
      - .offset:         216
        .size:           2
        .value_kind:     hidden_grid_dims
      - .offset:         240
        .size:           8
        .value_kind:     hidden_multigrid_sync_arg
      - .offset:         272
        .size:           4
        .value_kind:     hidden_dynamic_lds_size
    .group_segment_fixed_size: 0
    .kernarg_segment_align: 8
    .kernarg_segment_size: 408
    .language:       OpenCL C
    .language_version:
      - 2
      - 0
    .max_flat_workgroup_size: 512
    .name:           _ZN2mk6mk_fwdENS_4ArgsE
    .private_segment_fixed_size: 0
    .sgpr_count:     108
    .sgpr_spill_count: 5
    .symbol:         _ZN2mk6mk_fwdENS_4ArgsE.kd
    .uniform_work_group_size: 1
    .uses_dynamic_stack: false
    .vgpr_count:     256
    .vgpr_spill_count: 0
    .wavefront_size: 64
